# CONV loop with 16 channels per thread and iteration (two 16-byte loads per tap row, two 16-byte stores)
# speedup vs baseline: 1.0142x; 1.0068x over previous
.LBB0_1231:
	s_andn2_b64 vcc, exec, s[0:1]
	s_cbranch_vccnz .LBB0_1289
	s_cmp_gt_i32 s79, 9
	s_mov_b64 s[0:1], -1
	s_cbranch_scc0 .LBB0_1237
	v_mov_b32_e32 v0, s63
	ds_read_b32 v0, v0
	s_add_i32 s2, s91, 0x20050
	s_waitcnt lgkmcnt(0)
	v_readfirstlane_b32 s0, v0
	v_mov_b32_e32 v0, s89
	ds_read_b32 v0, v0
	s_waitcnt lgkmcnt(0)
	v_readfirstlane_b32 s1, v0
	v_mov_b32_e32 v0, s2
	ds_read_b32 v0, v0
	s_add_i32 s2, s91, 0x20054
	s_waitcnt lgkmcnt(0)
	v_readfirstlane_b32 s4, v0
	v_mov_b32_e32 v0, s2
	ds_read_b32 v0, v0
	s_add_i32 s2, s91, 0x20058
	s_waitcnt lgkmcnt(0)
	v_readfirstlane_b32 s5, v0
	v_mov_b32_e32 v0, s2
	ds_read_b32 v0, v0
	s_add_i32 s2, s91, 0x2005c
	s_waitcnt lgkmcnt(0)
	v_readfirstlane_b32 s6, v0
	v_mov_b32_e32 v0, s2
	ds_read_b32 v0, v0
	s_mov_b32 s2, 0x420000
	v_cmp_gt_i32_e32 vcc, s2, v160
	s_waitcnt lgkmcnt(0)
	v_readfirstlane_b32 s7, v0
	s_and_saveexec_b64 s[2:3], vcc
	s_cbranch_execz .LBB0_1236
	v_readlane_b32 s9, v254, 26
	s_lshl_b32 s8, s9, 12
	s_lshl_b32 s9, s9, 14
	s_add_u32 s4, s4, s9
	s_addc_u32 s5, s5, 0
	s_add_u32 s6, s6, s8
	s_addc_u32 s7, s7, 0
	s_add_u32 s8, s0, 0x4200000
	s_addc_u32 s9, s1, 0
	s_add_u32 s10, s0, 0x8400000
	s_addc_u32 s11, s1, 0
	s_mov_b64 s[12:13], 0
	v_mov_b32_e32 v12, v160
	v_lshlrev_b32_e32 v62, 4, v160
	v_and_b32_e32 v62, 0x3f0, v62
	v_lshlrev_b32_e32 v62, 2, v62
	v_add_u32_e32 v63, 0x1000, v62
	v_add_u32_e32 v144, 0x2000, v62
	v_add_u32_e32 v145, 0x3000, v62
	global_load_dwordx4 v[64:67], v62, s[6:7]
	global_load_dwordx4 v[68:71], v62, s[6:7] offset:16
	global_load_dwordx4 v[72:75], v62, s[6:7] offset:32
	global_load_dwordx4 v[76:79], v62, s[6:7] offset:48
	global_load_dwordx4 v[80:83], v62, s[4:5]
	global_load_dwordx4 v[84:87], v62, s[4:5] offset:16
	global_load_dwordx4 v[88:91], v62, s[4:5] offset:32
	global_load_dwordx4 v[92:95], v62, s[4:5] offset:48
	global_load_dwordx4 v[96:99], v63, s[4:5]
	global_load_dwordx4 v[100:103], v63, s[4:5] offset:16
	global_load_dwordx4 v[104:107], v63, s[4:5] offset:32
	global_load_dwordx4 v[108:111], v63, s[4:5] offset:48
	global_load_dwordx4 v[112:115], v144, s[4:5]
	global_load_dwordx4 v[116:119], v144, s[4:5] offset:16
	global_load_dwordx4 v[120:123], v144, s[4:5] offset:32
	global_load_dwordx4 v[124:127], v144, s[4:5] offset:48
	global_load_dwordx4 v[128:131], v145, s[4:5]
	global_load_dwordx4 v[132:135], v145, s[4:5] offset:16
	global_load_dwordx4 v[136:139], v145, s[4:5] offset:32
	global_load_dwordx4 v[140:143], v145, s[4:5] offset:48
.LBB0_1235:
	v_ashrrev_i32_e32 v0, 6, v12
	v_cmp_gt_i32_e32 vcc, s92, v0
	v_mov_b32_e32 v2, 0x7fffff00
	v_mov_b32_e32 v3, 0xffffe000
	v_cndmask_b32_e32 v2, v2, v3, vcc
	v_cndmask_b32_e32 v3, v227, v238, vcc
	v_cndmask_b32_e32 v13, v155, v253, vcc
	v_and_b32_e32 v28, v3, v0
	v_and_b32_e32 v25, v2, v0
	v_lshlrev_b32_e32 v1, 4, v12
	v_and_b32_e32 v1, 0x3f0, v1
	v_lshlrev_b32_e32 v2, 1, v1
	v_mov_b32_e32 v3, v153
	v_lshl_add_u64 v[6:7], s[8:9], 0, v[2:3]
	v_add_u32_e32 v30, -2, v28
	v_cmp_lt_u32_e32 vcc, 1, v28
	v_cmp_lt_u32_e64 s[0:1], v30, v13
	s_and_b64 vcc, vcc, s[0:1]
	v_cndmask_b32_e32 v30, v28, v30, vcc
	v_cndmask_b32_e64 v40, 0, 1.0, vcc
	v_add_u32_e32 v30, v30, v25
	v_ashrrev_i32_e32 v31, 31, v30
	v_lshlrev_b64 v[30:31], 11, v[30:31]
	v_lshl_add_u64 v[30:31], v[6:7], 0, v[30:31]
	global_load_dwordx4 v[166:169], v[30:31], off
	global_load_dwordx4 v[170:173], v[30:31], off offset:16
	v_add_u32_e32 v32, -1, v28
	v_cmp_lt_u32_e32 vcc, v32, v13
	s_nop 1
	v_cndmask_b32_e64 v42, 0, 1.0, vcc
	v_add_u32_e32 v18, v25, v28
	s_nop 1
	v_subbrev_co_u32_e64 v32, s[0:1], 0, v18, vcc
	v_ashrrev_i32_e32 v33, 31, v32
	v_lshlrev_b64 v[32:33], 11, v[32:33]
	v_lshl_add_u64 v[32:33], v[6:7], 0, v[32:33]
	global_load_dwordx4 v[174:177], v[32:33], off
	global_load_dwordx4 v[178:181], v[32:33], off offset:16
	v_cmp_lt_u32_e32 vcc, v28, v13
	s_nop 1
	v_cndmask_b32_e64 v44, 0, 1.0, vcc
	v_ashrrev_i32_e32 v19, 31, v18
	v_lshlrev_b64 v[34:35], 11, v[18:19]
	v_lshl_add_u64 v[34:35], v[6:7], 0, v[34:35]
	global_load_dwordx4 v[182:185], v[34:35], off
	global_load_dwordx4 v[186:189], v[34:35], off offset:16
	v_add_u32_e32 v36, 1, v28
	v_cmp_lt_u32_e32 vcc, v36, v13
	s_nop 1
	v_cndmask_b32_e32 v36, v28, v36, vcc
	v_cndmask_b32_e64 v46, 0, 1.0, vcc
	v_add_u32_e32 v36, v36, v25
	v_ashrrev_i32_e32 v37, 31, v36
	v_lshlrev_b64 v[36:37], 11, v[36:37]
	v_lshl_add_u64 v[36:37], v[6:7], 0, v[36:37]
	global_load_dwordx4 v[190:193], v[36:37], off
	global_load_dwordx4 v[194:197], v[36:37], off offset:16
	v_ashrrev_i32_e32 v1, 31, v0
	v_lshlrev_b64 v[0:1], 11, v[0:1]
	v_lshl_add_u64 v[0:1], s[10:11], 0, v[0:1]
	v_lshl_add_u64 v[0:1], v[0:1], 0, v[2:3]
	v_add_u32_e32 v12, s24, v12
	v_cmp_lt_i32_e32 vcc, 0x107fff, v12
	s_nop 1
	s_or_b64 s[12:13], vcc, s[12:13]
	s_waitcnt vmcnt(6)
	v_lshlrev_b32_e32 v38, 16, v166
	v_and_b32_e32 v39, 0xffff0000, v166
	v_lshlrev_b32_e32 v48, 16, v167
	v_and_b32_e32 v49, 0xffff0000, v167
	v_lshlrev_b32_e32 v50, 16, v168
	v_and_b32_e32 v51, 0xffff0000, v168
	v_lshlrev_b32_e32 v52, 16, v169
	v_and_b32_e32 v53, 0xffff0000, v169
	v_lshlrev_b32_e32 v54, 16, v170
	v_and_b32_e32 v55, 0xffff0000, v170
	v_lshlrev_b32_e32 v56, 16, v171
	v_and_b32_e32 v57, 0xffff0000, v171
	v_lshlrev_b32_e32 v58, 16, v172
	v_and_b32_e32 v59, 0xffff0000, v172
	v_lshlrev_b32_e32 v60, 16, v173
	v_and_b32_e32 v61, 0xffff0000, v173
	v_pk_mul_f32 v[198:199], v[80:81], v[38:39]
	v_pk_fma_f32 v[198:199], v[198:199], v[40:41], v[64:65] op_sel_hi:[1,0,1]
	v_pk_mul_f32 v[200:201], v[82:83], v[48:49]
	v_pk_fma_f32 v[200:201], v[200:201], v[40:41], v[66:67] op_sel_hi:[1,0,1]
	v_pk_mul_f32 v[202:203], v[84:85], v[50:51]
	v_pk_fma_f32 v[202:203], v[202:203], v[40:41], v[68:69] op_sel_hi:[1,0,1]
	v_pk_mul_f32 v[204:205], v[86:87], v[52:53]
	v_pk_fma_f32 v[204:205], v[204:205], v[40:41], v[70:71] op_sel_hi:[1,0,1]
	v_pk_mul_f32 v[206:207], v[88:89], v[54:55]
	v_pk_fma_f32 v[206:207], v[206:207], v[40:41], v[72:73] op_sel_hi:[1,0,1]
	v_pk_mul_f32 v[208:209], v[90:91], v[56:57]
	v_pk_fma_f32 v[208:209], v[208:209], v[40:41], v[74:75] op_sel_hi:[1,0,1]
	v_pk_mul_f32 v[210:211], v[92:93], v[58:59]
	v_pk_fma_f32 v[210:211], v[210:211], v[40:41], v[76:77] op_sel_hi:[1,0,1]
	v_pk_mul_f32 v[212:213], v[94:95], v[60:61]
	v_pk_fma_f32 v[212:213], v[212:213], v[40:41], v[78:79] op_sel_hi:[1,0,1]
	s_waitcnt vmcnt(4)
	v_lshlrev_b32_e32 v38, 16, v174
	v_and_b32_e32 v39, 0xffff0000, v174
	v_lshlrev_b32_e32 v48, 16, v175
	v_and_b32_e32 v49, 0xffff0000, v175
	v_lshlrev_b32_e32 v50, 16, v176
	v_and_b32_e32 v51, 0xffff0000, v176
	v_lshlrev_b32_e32 v52, 16, v177
	v_and_b32_e32 v53, 0xffff0000, v177
	v_lshlrev_b32_e32 v54, 16, v178
	v_and_b32_e32 v55, 0xffff0000, v178
	v_lshlrev_b32_e32 v56, 16, v179
	v_and_b32_e32 v57, 0xffff0000, v179
	v_lshlrev_b32_e32 v58, 16, v180
	v_and_b32_e32 v59, 0xffff0000, v180
	v_lshlrev_b32_e32 v60, 16, v181
	v_and_b32_e32 v61, 0xffff0000, v181
	v_pk_mul_f32 v[214:215], v[96:97], v[38:39]
	v_pk_fma_f32 v[198:199], v[42:43], v[214:215], v[198:199] op_sel_hi:[0,1,1]
	v_pk_mul_f32 v[216:217], v[98:99], v[48:49]
	v_pk_fma_f32 v[200:201], v[42:43], v[216:217], v[200:201] op_sel_hi:[0,1,1]
	v_pk_mul_f32 v[218:219], v[100:101], v[50:51]
	v_pk_fma_f32 v[202:203], v[42:43], v[218:219], v[202:203] op_sel_hi:[0,1,1]
	v_pk_mul_f32 v[220:221], v[102:103], v[52:53]
	v_pk_fma_f32 v[204:205], v[42:43], v[220:221], v[204:205] op_sel_hi:[0,1,1]
	v_pk_mul_f32 v[222:223], v[104:105], v[54:55]
	v_pk_fma_f32 v[206:207], v[42:43], v[222:223], v[206:207] op_sel_hi:[0,1,1]
	v_pk_mul_f32 v[224:225], v[106:107], v[56:57]
	v_pk_fma_f32 v[208:209], v[42:43], v[224:225], v[208:209] op_sel_hi:[0,1,1]
	v_pk_mul_f32 v[146:147], v[108:109], v[58:59]
	v_pk_fma_f32 v[210:211], v[42:43], v[146:147], v[210:211] op_sel_hi:[0,1,1]
	v_pk_mul_f32 v[148:149], v[110:111], v[60:61]
	v_pk_fma_f32 v[212:213], v[42:43], v[148:149], v[212:213] op_sel_hi:[0,1,1]
	s_waitcnt vmcnt(2)
	v_lshlrev_b32_e32 v38, 16, v182
	v_and_b32_e32 v39, 0xffff0000, v182
	v_lshlrev_b32_e32 v48, 16, v183
	v_and_b32_e32 v49, 0xffff0000, v183
	v_lshlrev_b32_e32 v50, 16, v184
	v_and_b32_e32 v51, 0xffff0000, v184
	v_lshlrev_b32_e32 v52, 16, v185
	v_and_b32_e32 v53, 0xffff0000, v185
	v_lshlrev_b32_e32 v54, 16, v186
	v_and_b32_e32 v55, 0xffff0000, v186
	v_lshlrev_b32_e32 v56, 16, v187
	v_and_b32_e32 v57, 0xffff0000, v187
	v_lshlrev_b32_e32 v58, 16, v188
	v_and_b32_e32 v59, 0xffff0000, v188
	v_lshlrev_b32_e32 v60, 16, v189
	v_and_b32_e32 v61, 0xffff0000, v189
	v_pk_mul_f32 v[214:215], v[112:113], v[38:39]
	v_pk_fma_f32 v[198:199], v[44:45], v[214:215], v[198:199] op_sel_hi:[0,1,1]
	v_pk_mul_f32 v[216:217], v[114:115], v[48:49]
	v_pk_fma_f32 v[200:201], v[44:45], v[216:217], v[200:201] op_sel_hi:[0,1,1]
	v_pk_mul_f32 v[218:219], v[116:117], v[50:51]
	v_pk_fma_f32 v[202:203], v[44:45], v[218:219], v[202:203] op_sel_hi:[0,1,1]
	v_pk_mul_f32 v[220:221], v[118:119], v[52:53]
	v_pk_fma_f32 v[204:205], v[44:45], v[220:221], v[204:205] op_sel_hi:[0,1,1]
	v_pk_mul_f32 v[222:223], v[120:121], v[54:55]
	v_pk_fma_f32 v[206:207], v[44:45], v[222:223], v[206:207] op_sel_hi:[0,1,1]
	v_pk_mul_f32 v[224:225], v[122:123], v[56:57]
	v_pk_fma_f32 v[208:209], v[44:45], v[224:225], v[208:209] op_sel_hi:[0,1,1]
	v_pk_mul_f32 v[146:147], v[124:125], v[58:59]
	v_pk_fma_f32 v[210:211], v[44:45], v[146:147], v[210:211] op_sel_hi:[0,1,1]
	v_pk_mul_f32 v[148:149], v[126:127], v[60:61]
	v_pk_fma_f32 v[212:213], v[44:45], v[148:149], v[212:213] op_sel_hi:[0,1,1]
	s_waitcnt vmcnt(0)
	v_lshlrev_b32_e32 v38, 16, v190
	v_and_b32_e32 v39, 0xffff0000, v190
	v_lshlrev_b32_e32 v48, 16, v191
	v_and_b32_e32 v49, 0xffff0000, v191
	v_lshlrev_b32_e32 v50, 16, v192
	v_and_b32_e32 v51, 0xffff0000, v192
	v_lshlrev_b32_e32 v52, 16, v193
	v_and_b32_e32 v53, 0xffff0000, v193
	v_lshlrev_b32_e32 v54, 16, v194
	v_and_b32_e32 v55, 0xffff0000, v194
	v_lshlrev_b32_e32 v56, 16, v195
	v_and_b32_e32 v57, 0xffff0000, v195
	v_lshlrev_b32_e32 v58, 16, v196
	v_and_b32_e32 v59, 0xffff0000, v196
	v_lshlrev_b32_e32 v60, 16, v197
	v_and_b32_e32 v61, 0xffff0000, v197
	v_pk_mul_f32 v[214:215], v[128:129], v[38:39]
	v_pk_fma_f32 v[198:199], v[46:47], v[214:215], v[198:199] op_sel_hi:[0,1,1]
	v_pk_mul_f32 v[216:217], v[130:131], v[48:49]
	v_pk_fma_f32 v[200:201], v[46:47], v[216:217], v[200:201] op_sel_hi:[0,1,1]
	v_pk_mul_f32 v[218:219], v[132:133], v[50:51]
	v_pk_fma_f32 v[202:203], v[46:47], v[218:219], v[202:203] op_sel_hi:[0,1,1]
	v_pk_mul_f32 v[220:221], v[134:135], v[52:53]
	v_pk_fma_f32 v[204:205], v[46:47], v[220:221], v[204:205] op_sel_hi:[0,1,1]
	v_pk_mul_f32 v[222:223], v[136:137], v[54:55]
	v_pk_fma_f32 v[206:207], v[46:47], v[222:223], v[206:207] op_sel_hi:[0,1,1]
	v_pk_mul_f32 v[224:225], v[138:139], v[56:57]
	v_pk_fma_f32 v[208:209], v[46:47], v[224:225], v[208:209] op_sel_hi:[0,1,1]
	v_pk_mul_f32 v[146:147], v[140:141], v[58:59]
	v_pk_fma_f32 v[210:211], v[46:47], v[146:147], v[210:211] op_sel_hi:[0,1,1]
	v_pk_mul_f32 v[148:149], v[142:143], v[60:61]
	v_pk_fma_f32 v[212:213], v[46:47], v[148:149], v[212:213] op_sel_hi:[0,1,1]
	v_cvt_pk_bf16_f32 v230, v198, v199
	v_cvt_pk_bf16_f32 v231, v200, v201
	v_cvt_pk_bf16_f32 v232, v202, v203
	v_cvt_pk_bf16_f32 v233, v204, v205
	v_cvt_pk_bf16_f32 v234, v206, v207
	v_cvt_pk_bf16_f32 v235, v208, v209
	v_cvt_pk_bf16_f32 v236, v210, v211
	v_cvt_pk_bf16_f32 v237, v212, v213
	global_store_dwordx4 v[0:1], v[230:233], off
	global_store_dwordx4 v[0:1], v[234:237], off offset:16
	s_andn2_b64 exec, exec, s[12:13]
	s_cbranch_execnz .LBB0_1235
